# P10 packed tiles, block visits: contiguous task chunks per wave, K/V fragments loaded once per visit and reused by all of the visit's query groups
# speedup vs baseline: 1.1103x; 1.0170x over previous
.LBB0_1317:
	s_or_b64 exec, exec, s[0:1]
	s_bcnt1_i32_b64 s0, vcc
	s_waitcnt lgkmcnt(0)
	s_add_i32 s0, s8, s0
	v_ashrrev_i32_e32 v219, 31, v218
	v_ashrrev_i32_e32 v215, 31, v214
	s_lshl_b32 s1, s10, 21
	s_add_u32 s8, s36, s1
	s_addc_u32 s9, s37, 0
	s_add_u32 s11, s40, s1
	s_addc_u32 s12, s41, 0
	s_movk_i32 s82, 0x660
	s_waitcnt lgkmcnt(0)
	s_barrier
	v_lshlrev_b32_e32 v2, 4, v199
	v_mov_b32_e32 v22, v218
	v_mov_b32_e32 v23, v4
	v_mov_b32_e32 v24, v9
	v_mov_b32_e32 v25, v10
	v_and_b32_e32 v18, 7, v226
	v_lshlrev_b32_e32 v18, 3, v18
	v_mov_b32_e32 v19, 0x110
	v_mul_u32_u24_e32 v19, v19, v200
	v_lshl_add_u32 v19, v206, 2, v19
	v_add_u32_e32 v19, 0x4000, v19
	v_lshl_add_u32 v20, v216, 1, v210
	v_mov_b32_e32 v31, 0x110
	v_mul_u32_u24_e32 v31, v31, v200
	v_add_u32_e32 v31, 0x4100, v31
	v_add_u32_e32 v31, v31, v206
	v_mov_b32_e32 v82, 0
	v_mov_b32_e32 v83, 0
	v_mov_b32_e32 v84, 0
	v_mov_b32_e32 v85, 0
	s_lshl_b32 s0, s77, 10
	s_add_i32 s0, s0, 0x4000
	v_add_u32_e32 v28, s0, v2
	v_add_u32_e32 v29, 0x10000, v28
	ds_write_b128 v28, v[82:85]
	ds_write_b128 v28, v[82:85] offset:8192
	ds_write_b128 v28, v[82:85] offset:16384
	ds_write_b128 v28, v[82:85] offset:24576
	ds_write_b128 v28, v[82:85] offset:32768
	ds_write_b128 v28, v[82:85] offset:40960
	ds_write_b128 v28, v[82:85] offset:49152
	ds_write_b128 v28, v[82:85] offset:57344
	ds_write_b128 v29, v[82:85]
	ds_write_b128 v29, v[82:85] offset:8192
	ds_write_b128 v29, v[82:85] offset:16384
	ds_write_b128 v29, v[82:85] offset:24576
	ds_write_b128 v29, v[82:85] offset:32768
	v_mov_b32_e32 v86, 0x1800
	ds_write_b32 v86, v82
	ds_write_b64 v86, v[82:83] offset:8
	s_lshl_b32 s90, s77, 8
	s_add_i32 s90, s90, 0x1e000
	v_lshl_add_u32 v122, v199, 2, s90
	ds_write_b32 v122, v82
	s_waitcnt lgkmcnt(0)
	s_barrier
	v_and_b32_e32 v102, 31, v199
	s_lshl_b32 s0, s77, 5
	v_add_u32_e32 v103, s0, v102
	s_mov_b64 s[58:59], exec
	v_cmp_gt_u32_e32 vcc, 32, v199
	s_and_b64 exec, exec, vcc
	v_lshlrev_b32_e32 v106, 3, v103
	ds_read_b64 v[104:105], v106
	s_waitcnt lgkmcnt(0)
	v_bcnt_u32_b32 v107, v104, 0
	v_bcnt_u32_b32 v107, v105, v107
	v_add_u32_e32 v108, 3, v107
	v_lshrrev_b32_e32 v108, 2, v108
	v_mov_b32_e32 v110, 0x1800
	ds_add_rtn_u32 v109, v110, v108
	s_waitcnt lgkmcnt(0)

.Lq_build_done:
	s_mov_b64 exec, s[58:59]
	s_waitcnt lgkmcnt(0)
	s_barrier
	v_mov_b32_e32 v110, 0x1800
	ds_read_b32 v111, v110
	s_waitcnt lgkmcnt(0)
	v_readfirstlane_b32 s0, v111
	s_mul_i32 s1, s0, s77
	s_lshr_b32 s1, s1, 3
	s_add_i32 s14, s77, 1
	s_mul_i32 s14, s0, s14
	s_lshr_b32 s14, s14, 3
	s_sub_i32 s10, s14, s1
	v_cmp_gt_u32_e32 vcc, s10, v199
	v_mov_b32_e32 v26, 0
	v_mov_b32_e32 v27, 0
	v_add_u32_e32 v112, s1, v199
	v_lshlrev_b32_e32 v113, 3, v112
	s_and_b64 exec, exec, vcc
	ds_read_b64 v[114:115], v113 offset:2048
	s_waitcnt lgkmcnt(0)
	v_mov_b32_e32 v26, v114
	v_mov_b32_e32 v27, v115
	s_mov_b64 exec, s[58:59]
	v_and_b32_e32 v116, 0xff, v26
	v_add_u32_e32 v117, -1, v199
	v_lshlrev_b32_e32 v117, 2, v117
	ds_bpermute_b32 v118, v117, v116
	s_waitcnt lgkmcnt(0)
	v_cmp_ne_u32_e64 s[14:15], v116, v118
	v_cmp_eq_u32_e64 s[30:31], 0, v199
	s_or_b64 s[14:15], s[14:15], s[30:31]
	s_and_b64 s[14:15], s[14:15], vcc
	s_bcnt1_i32_b64 s89, s[14:15]
	v_mbcnt_lo_u32_b32 v119, s14, 0
	v_mbcnt_hi_u32_b32 v119, s15, v119
	v_lshl_or_b32 v120, v199, 8, v116
	v_lshl_add_u32 v121, v119, 2, s90
	s_mov_b64 exec, s[14:15]
	ds_write_b32 v121, v120
	s_mov_b64 exec, s[58:59]
	s_waitcnt lgkmcnt(0)
	v_lshl_add_u32 v122, v199, 2, s90
	ds_read_b32 v33, v122
	s_waitcnt lgkmcnt(0)
	s_mov_b32 s52, 0
	s_mov_b32 s69, 0
	s_min_u32 s14, s69, 63
	s_nop 3
	v_readlane_b32 s30, v33, s14
	s_and_b32 s30, s30, 0xff
	s_lshl_b32 s30, s30, 13
	s_add_u32 s64, s11, s30
	s_addc_u32 s65, s12, 0
	s_add_u32 s66, s8, s30
	s_addc_u32 s67, s9, 0
	global_load_dwordx4 v[178:181], v2, s[64:65]
	global_load_dwordx4 v[174:177], v2, s[64:65] offset:1024
	global_load_dwordx4 v[170:173], v2, s[64:65] offset:2048
	global_load_dwordx4 v[166:169], v2, s[64:65] offset:3072
	global_load_dwordx4 v[146:149], v2, s[66:67]
	global_load_dwordx4 v[142:145], v2, s[66:67] offset:1024
	global_load_dwordx4 v[126:129], v2, s[66:67] offset:2048
	global_load_dwordx4 v[114:117], v2, s[66:67] offset:3072
	s_mov_b32 s69, 0
	s_min_u32 s14, s69, 63
	s_nop 3
	v_readlane_b32 s30, v26, s14
	v_readlane_b32 s31, v27, s14
	v_bfe_u32 v28, s31, v18, 8
	v_lshl_add_u32 v29, s99, 6, v28
	v_mad_u32_u24 v29, v29, s47, v20
	global_load_dwordx4 v[238:241], v29, s[20:21]
	global_load_dwordx4 v[242:245], v29, s[20:21] offset:32
	global_load_dwordx4 v[246:249], v29, s[20:21] offset:64
	global_load_dwordx4 v[250:253], v29, s[20:21] offset:96
	s_mov_b32 s69, 0
	s_min_u32 s14, s69, 63
	s_nop 3
	v_readlane_b32 s30, v33, s14
	s_and_b32 s30, s30, 0xff
	s_lshl_b32 s30, s30, 13
	s_or_b32 s30, s30, 0x1000
	s_add_u32 s64, s11, s30
	s_addc_u32 s65, s12, 0
	s_add_u32 s66, s8, s30
	s_addc_u32 s67, s9, 0
	global_load_dwordx4 v[162:165], v2, s[64:65]
	global_load_dwordx4 v[154:157], v2, s[64:65] offset:1024
	global_load_dwordx4 v[150:153], v2, s[64:65] offset:2048
	global_load_dwordx4 v[158:161], v2, s[64:65] offset:3072
	global_load_dwordx4 v[138:141], v2, s[66:67]
	global_load_dwordx4 v[122:125], v2, s[66:67] offset:1024
	global_load_dwordx4 v[110:113], v2, s[66:67] offset:2048
	global_load_dwordx4 v[106:109], v2, s[66:67] offset:3072
	s_mov_b32 s69, 1
	s_min_u32 s14, s69, 63
	s_nop 3
	v_readlane_b32 s30, v33, s14
	s_and_b32 s30, s30, 0xff
	s_lshl_b32 s30, s30, 13
	s_add_u32 s64, s11, s30
	s_addc_u32 s65, s12, 0
	s_add_u32 s66, s8, s30
	s_addc_u32 s67, s9, 0
	global_load_dwordx4 v[194:197], v2, s[64:65]
	global_load_dwordx4 v[190:193], v2, s[64:65] offset:1024
	global_load_dwordx4 v[186:189], v2, s[64:65] offset:2048
	global_load_dwordx4 v[182:185], v2, s[64:65] offset:3072
	global_load_dwordx4 v[134:137], v2, s[66:67]
	global_load_dwordx4 v[130:133], v2, s[66:67] offset:1024
	global_load_dwordx4 v[118:121], v2, s[66:67] offset:2048
	global_load_dwordx4 v[102:105], v2, s[66:67] offset:3072
.Lq_loop:
.Lq_visit_k0:
	s_lshr_b32 s84, s52, 1
	s_add_i32 s84, s84, 0
	s_cmp_ge_u32 s84, s89
	s_cbranch_scc1 .Lq_loop_end
	s_min_u32 s14, s84, 63
	s_nop 3
	v_readlane_b32 s0, v33, s14
	s_and_b32 s100, s0, 0xff
	s_lshr_b32 s68, s0, 8
	s_mov_b32 s91, s68
	s_add_i32 s1, s84, 1
	s_min_u32 s14, s1, 63
	s_nop 3
	v_readlane_b32 s86, v33, s14
	s_lshr_b32 s86, s86, 8
	s_cmp_ge_u32 s1, s89
	s_cselect_b32 s86, s10, s86
	s_add_i32 s87, s84, 1
	s_add_i32 s88, s84, 2
.Lq_tk_k0:
	s_min_u32 s14, s68, 63
	s_nop 3
	v_readlane_b32 s56, v26, s14
	v_readlane_b32 s57, v27, s14
	s_lshr_b32 s0, s56, 8
	s_lshl_b32 s18, 1, s0
	s_add_i32 s18, s18, -1
	s_add_i32 s85, s68, 1
	s_cmp_eq_u32 s68, s91
	s_cbranch_scc1 .Lq_w16_k0
	s_waitcnt vmcnt(0)
	s_branch .Lq_wd_k0
.Lq_w16_k0:
	s_waitcnt vmcnt(16)
.Lq_wd_k0:
	v_mov_b32_e32 v4, v238
	v_mov_b32_e32 v5, v239
	v_mov_b32_e32 v6, v240
	v_mov_b32_e32 v7, v241
	v_mov_b32_e32 v8, v242
	v_mov_b32_e32 v9, v243
	v_mov_b32_e32 v10, v244
	v_mov_b32_e32 v11, v245
	v_mov_b32_e32 v12, v246
	v_mov_b32_e32 v13, v247
	v_mov_b32_e32 v14, v248
	v_mov_b32_e32 v15, v249
	v_mov_b32_e32 v98, v250
	v_mov_b32_e32 v99, v251
	v_mov_b32_e32 v100, v252
	v_mov_b32_e32 v101, v253
	v_bfe_u32 v28, s57, v18, 8
	v_lshl_add_u32 v218, s99, 6, v28
	v_mad_u32_u24 v21, v28, s82, v19
	v_mad_u32_u24 v32, v28, s82, v31
	v_and_b32_e32 v29, s18, v230
	v_cmp_ne_u32_e64 s[54:55], 0, v29
	s_and_b64 s[54:55], s[54:55], s[6:7]
	s_min_u32 s14, s85, 63
	s_nop 3
	v_readlane_b32 s30, v26, s14
	v_readlane_b32 s31, v27, s14
	v_bfe_u32 v28, s31, v18, 8
	v_lshl_add_u32 v29, s99, 6, v28
	v_mad_u32_u24 v29, v29, s47, v20
	global_load_dwordx4 v[238:241], v29, s[20:21]
	global_load_dwordx4 v[242:245], v29, s[20:21] offset:32
	global_load_dwordx4 v[246:249], v29, s[20:21] offset:64
	global_load_dwordx4 v[250:253], v29, s[20:21] offset:96
	s_lshl_b32 s0, s100, 6
	v_or_b32_e32 v237, s0, v206
	v_mov_b32_e32 v221, 0
	s_cmp_lg_u32 s100, s99
	s_cbranch_scc1 .Lq_s0n_k0
	v_and_b32_e32 v82, s18, v230
	v_cmp_ne_u32_e32 vcc, 0, v82
	s_and_b64 vcc, s[6:7], vcc
	v_mov_b32 v83, 0
	v_or_b32_e32 v16, 2, v237
	v_cndmask_b32_e32 v82, v236, v222, vcc
	v_sub_f32_e32 v82, v83, v82
	v_mov_b32_e32 v83, v82
	v_mov_b32_e32 v84, v82
	v_mov_b32_e32 v85, v82
	v_mov_b32_e32 v86, v82
	v_mov_b32_e32 v87, v82
	v_mov_b32_e32 v88, v82
	v_mov_b32_e32 v89, v82
	v_mov_b32_e32 v90, v82
	v_mov_b32_e32 v91, v82
	v_mov_b32_e32 v92, v82
	v_mov_b32_e32 v93, v82
	v_mov_b32_e32 v94, v82
	v_mov_b32_e32 v95, v82
	v_mov_b32_e32 v96, v82
	v_mov_b32_e32 v97, v82
	v_cmp_le_i32_e32 vcc, v237, v218
	v_or_b32_e32 v17, 3, v237
	v_mfma_f32_32x32x16_bf16 v[82:97], v[178:181], v[4:7], v[82:97]
	v_or_b32_e32 v30, 8, v237
	v_mfma_f32_32x32x16_bf16 v[82:97], v[174:177], v[8:11], v[82:97]
	v_mfma_f32_32x32x16_bf16 v[82:97], v[170:173], v[12:15], v[82:97]
	v_mfma_f32_32x32x16_bf16 v[82:97], v[166:169], v[98:101], v[82:97]
	s_nop 11
	v_exp_f32_e32 v82, v82
	v_exp_f32_e32 v83, v83
	v_exp_f32_e32 v84, v84
	v_exp_f32_e32 v85, v85
	v_exp_f32_e32 v86, v86
	v_cndmask_b32_e32 v82, 0, v82, vcc
	v_cmp_lt_i32_e32 vcc, v237, v218
	v_exp_f32_e32 v87, v87
	v_exp_f32_e32 v88, v88
	v_cndmask_b32_e32 v83, 0, v83, vcc
	v_cmp_le_i32_e32 vcc, v16, v218
	v_or_b32_e32 v16, 9, v237
	v_exp_f32_e32 v89, v89
	v_cndmask_b32_e32 v84, 0, v84, vcc
	v_cmp_le_i32_e32 vcc, v17, v218
	v_exp_f32_e32 v90, v90
	v_exp_f32_e32 v91, v91
	v_cndmask_b32_e32 v85, 0, v85, vcc
	v_cmp_le_i32_e32 vcc, v30, v218
	v_add_f32_e32 v221, v221, v82
	v_exp_f32_e32 v92, v92
	v_cndmask_b32_e32 v86, 0, v86, vcc
	v_cmp_le_i32_e32 vcc, v16, v218
	v_or_b32_e32 v16, 10, v237
	v_add_f32_e32 v221, v83, v221
	v_cndmask_b32_e32 v87, 0, v87, vcc
	v_cmp_le_i32_e32 vcc, v16, v218
	v_or_b32_e32 v16, 11, v237
	v_exp_f32_e32 v93, v93
	v_cndmask_b32_e32 v88, 0, v88, vcc
	v_cmp_le_i32_e32 vcc, v16, v218
	v_or_b32_e32 v16, 16, v237
	v_add_f32_e32 v221, v84, v221
	v_cndmask_b32_e32 v89, 0, v89, vcc
	v_cmp_le_i32_e32 vcc, v16, v218
	v_or_b32_e32 v16, 17, v237
	v_exp_f32_e32 v94, v94
	v_cndmask_b32_e32 v90, 0, v90, vcc
	v_cmp_le_i32_e32 vcc, v16, v218
	v_or_b32_e32 v16, 18, v237
	v_add_f32_e32 v221, v85, v221
	v_cndmask_b32_e32 v91, 0, v91, vcc
	v_cmp_le_i32_e32 vcc, v16, v218
	v_or_b32_e32 v16, 19, v237
	v_exp_f32_e32 v95, v95
	v_add_f32_e32 v221, v86, v221
	v_cndmask_b32_e32 v92, 0, v92, vcc
	v_cmp_le_i32_e32 vcc, v16, v218
	v_or_b32_e32 v16, 24, v237
	v_cvt_pk_bf16_f32 v82, v82, v83
	v_cvt_pk_bf16_f32 v83, v84, v85
	v_cvt_pk_bf16_f32 v84, v86, v87
	v_cvt_pk_bf16_f32 v85, v88, v89
	v_add_f32_e32 v221, v87, v221
	v_cndmask_b32_e32 v93, 0, v93, vcc
	v_cmp_le_i32_e32 vcc, v16, v218
	v_or_b32_e32 v16, 25, v237
	v_mfma_f32_32x32x16_bf16 v[66:81], v[146:149], v[82:85], 0
	v_add_f32_e32 v221, v88, v221
	v_cndmask_b32_e32 v94, 0, v94, vcc
	v_exp_f32_e32 v86, v96
	v_cmp_le_i32_e32 vcc, v16, v218
	v_or_b32_e32 v88, 26, v237
	v_add_f32_e32 v221, v89, v221
	v_cndmask_b32_e32 v87, 0, v95, vcc
	v_mfma_f32_32x32x16_bf16 v[50:65], v[142:145], v[82:85], 0
	v_cmp_le_i32_e32 vcc, v88, v218
	v_exp_f32_e32 v88, v97
	v_or_b32_e32 v82, 27, v237
	v_cndmask_b32_e32 v86, 0, v86, vcc
	v_cmp_le_i32_e32 vcc, v82, v218
	v_cvt_pk_bf16_f32 v82, v90, v91
	v_cvt_pk_bf16_f32 v83, v92, v93
	v_cndmask_b32_e32 v88, 0, v88, vcc
	v_cvt_pk_bf16_f32 v84, v94, v87
	v_cvt_pk_bf16_f32 v85, v86, v88
	v_add_f32_e32 v221, v90, v221
	v_add_f32_e32 v89, v91, v221
	v_mfma_f32_32x32x16_bf16 v[66:81], v[126:129], v[82:85], v[66:81]
	v_add_f32_e32 v89, v92, v89
	v_add_f32_e32 v89, v93, v89
	v_add_f32_e32 v89, v94, v89
	v_add_f32_e32 v87, v87, v89
	v_add_f32_e32 v86, v86, v87
	v_add_f32_e32 v221, v88, v86
	v_mfma_f32_32x32x16_bf16 v[50:65], v[114:117], v[82:85], v[50:65]
	s_branch .Lq_s0d_k0

.Lq_s0d_k0:
	s_cmp_lg_u32 s85, s86
	s_cbranch_scc1 .Lq_nl0_k0
	s_min_u32 s14, s87, 63
	s_nop 3
	v_readlane_b32 s30, v33, s14
	s_and_b32 s30, s30, 0xff
	s_lshl_b32 s30, s30, 13
	s_or_b32 s30, s30, 0x1000
	s_add_u32 s64, s11, s30
	s_addc_u32 s65, s12, 0
	s_add_u32 s66, s8, s30
	s_addc_u32 s67, s9, 0
	global_load_dwordx4 v[178:181], v2, s[64:65]
	global_load_dwordx4 v[174:177], v2, s[64:65] offset:1024
	global_load_dwordx4 v[170:173], v2, s[64:65] offset:2048
	global_load_dwordx4 v[166:169], v2, s[64:65] offset:3072
	global_load_dwordx4 v[146:149], v2, s[66:67]
	global_load_dwordx4 v[142:145], v2, s[66:67] offset:1024
	global_load_dwordx4 v[126:129], v2, s[66:67] offset:2048
	global_load_dwordx4 v[114:117], v2, s[66:67] offset:3072
	s_waitcnt vmcnt(20)
	s_branch .Lq_nl0d_k0
.Lq_nl0_k0:
	s_waitcnt vmcnt(12)
.Lq_nl0d_k0:
	s_lshl_b32 s0, s100, 6
	s_or_b32 s0, s0, 32
	v_or_b32_e32 v237, s0, v206
	s_cmp_lg_u32 s100, s99
	s_cbranch_scc1 .Lq_s1n_k0
	v_and_b32_e32 v82, s18, v230
	v_cmp_ne_u32_e32 vcc, 0, v82
	s_and_b64 vcc, s[6:7], vcc
	v_mov_b32 v83, 0
	v_or_b32_e32 v16, 2, v237
	v_cndmask_b32_e32 v82, v236, v222, vcc
	v_sub_f32_e32 v82, v83, v82
	v_mov_b32_e32 v83, v82
	v_mov_b32_e32 v84, v82
	v_mov_b32_e32 v85, v82
	v_mov_b32_e32 v86, v82
	v_mov_b32_e32 v87, v82
	v_mov_b32_e32 v88, v82
	v_mov_b32_e32 v89, v82
	v_mov_b32_e32 v90, v82
	v_mov_b32_e32 v91, v82
	v_mov_b32_e32 v92, v82
	v_mov_b32_e32 v93, v82
	v_mov_b32_e32 v94, v82
	v_mov_b32_e32 v95, v82
	v_mov_b32_e32 v96, v82
	v_mov_b32_e32 v97, v82
	v_cmp_le_i32_e32 vcc, v237, v218
	v_or_b32_e32 v17, 3, v237
	v_mfma_f32_32x32x16_bf16 v[82:97], v[162:165], v[4:7], v[82:97]
	v_or_b32_e32 v30, 8, v237
	v_mfma_f32_32x32x16_bf16 v[82:97], v[154:157], v[8:11], v[82:97]
	v_mfma_f32_32x32x16_bf16 v[82:97], v[150:153], v[12:15], v[82:97]
	v_mfma_f32_32x32x16_bf16 v[82:97], v[158:161], v[98:101], v[82:97]
	s_nop 11
	v_exp_f32_e32 v82, v82
	v_exp_f32_e32 v83, v83
	v_exp_f32_e32 v84, v84
	v_exp_f32_e32 v85, v85
	v_exp_f32_e32 v86, v86
	v_cndmask_b32_e32 v82, 0, v82, vcc
	v_cmp_lt_i32_e32 vcc, v237, v218
	v_exp_f32_e32 v87, v87
	v_exp_f32_e32 v88, v88
	v_cndmask_b32_e32 v83, 0, v83, vcc
	v_cmp_le_i32_e32 vcc, v16, v218
	v_or_b32_e32 v16, 9, v237
	v_exp_f32_e32 v89, v89
	v_cndmask_b32_e32 v84, 0, v84, vcc
	v_cmp_le_i32_e32 vcc, v17, v218
	v_exp_f32_e32 v90, v90
	v_exp_f32_e32 v91, v91
	v_cndmask_b32_e32 v85, 0, v85, vcc
	v_cmp_le_i32_e32 vcc, v30, v218
	v_add_f32_e32 v221, v221, v82
	v_exp_f32_e32 v92, v92
	v_cndmask_b32_e32 v86, 0, v86, vcc
	v_cmp_le_i32_e32 vcc, v16, v218
	v_or_b32_e32 v16, 10, v237
	v_add_f32_e32 v221, v83, v221
	v_cndmask_b32_e32 v87, 0, v87, vcc
	v_cmp_le_i32_e32 vcc, v16, v218
	v_or_b32_e32 v16, 11, v237
	v_exp_f32_e32 v93, v93
	v_cndmask_b32_e32 v88, 0, v88, vcc
	v_cmp_le_i32_e32 vcc, v16, v218
	v_or_b32_e32 v16, 16, v237
	v_add_f32_e32 v221, v84, v221
	v_cndmask_b32_e32 v89, 0, v89, vcc
	v_cmp_le_i32_e32 vcc, v16, v218
	v_or_b32_e32 v16, 17, v237
	v_exp_f32_e32 v94, v94
	v_cndmask_b32_e32 v90, 0, v90, vcc
	v_cmp_le_i32_e32 vcc, v16, v218
	v_or_b32_e32 v16, 18, v237
	v_add_f32_e32 v221, v85, v221
	v_cndmask_b32_e32 v91, 0, v91, vcc
	v_cmp_le_i32_e32 vcc, v16, v218
	v_or_b32_e32 v16, 19, v237
	v_exp_f32_e32 v95, v95
	v_add_f32_e32 v221, v86, v221
	v_cndmask_b32_e32 v92, 0, v92, vcc
	v_cmp_le_i32_e32 vcc, v16, v218
	v_or_b32_e32 v16, 24, v237
	v_cvt_pk_bf16_f32 v82, v82, v83
	v_cvt_pk_bf16_f32 v83, v84, v85
	v_cvt_pk_bf16_f32 v84, v86, v87
	v_cvt_pk_bf16_f32 v85, v88, v89
	v_add_f32_e32 v221, v87, v221
	v_cndmask_b32_e32 v93, 0, v93, vcc
	v_cmp_le_i32_e32 vcc, v16, v218
	v_or_b32_e32 v16, 25, v237
	v_mfma_f32_32x32x16_bf16 v[66:81], v[138:141], v[82:85], v[66:81]
	v_add_f32_e32 v221, v88, v221
	v_cndmask_b32_e32 v94, 0, v94, vcc
	v_exp_f32_e32 v86, v96
	v_cmp_le_i32_e32 vcc, v16, v218
	v_or_b32_e32 v88, 26, v237
	v_add_f32_e32 v221, v89, v221
	v_cndmask_b32_e32 v87, 0, v95, vcc
	v_mfma_f32_32x32x16_bf16 v[50:65], v[122:125], v[82:85], v[50:65]
	v_cmp_le_i32_e32 vcc, v88, v218
	v_exp_f32_e32 v88, v97
	v_or_b32_e32 v82, 27, v237
	v_cndmask_b32_e32 v86, 0, v86, vcc
	v_cmp_le_i32_e32 vcc, v82, v218
	v_cvt_pk_bf16_f32 v82, v90, v91
	v_cvt_pk_bf16_f32 v83, v92, v93
	v_cndmask_b32_e32 v88, 0, v88, vcc
	v_cvt_pk_bf16_f32 v84, v94, v87
	v_cvt_pk_bf16_f32 v85, v86, v88
	v_add_f32_e32 v221, v90, v221
	v_add_f32_e32 v89, v91, v221
	v_mfma_f32_32x32x16_bf16 v[66:81], v[110:113], v[82:85], v[66:81]
	v_add_f32_e32 v89, v92, v89
	v_add_f32_e32 v89, v93, v89
	v_add_f32_e32 v89, v94, v89
	v_add_f32_e32 v87, v87, v89
	v_add_f32_e32 v86, v86, v87
	v_add_f32_e32 v221, v88, v86
	v_mfma_f32_32x32x16_bf16 v[50:65], v[106:109], v[82:85], v[50:65]
	s_branch .Lq_s1d_k0

.Lq_s1d_k0:
	s_mov_b64 s[60:61], 0
	s_lshr_b32 s0, s56, 8
	s_cmp_gt_u32 s0, 0
	s_cbranch_scc0 .Lq_m0_k0
	s_bfe_u32 s1, s57, 0x80000
	s_bitset1_b64 s[60:61], s1

.Lq_m3_k0:
	s_mov_b64 s[58:59], exec
	v_mov_b32_e32 v30, 0x1808
.Lq_lock_k0:
	s_mov_b64 exec, 1
	v_mov_b32_e32 v16, s60
	v_mov_b32_e32 v17, s61
	ds_or_rtn_b64 v[28:29], v30, v[16:17]
	s_waitcnt lgkmcnt(0)
	v_readfirstlane_b32 s62, v28
	v_readfirstlane_b32 s63, v29
	s_and_b64 s[64:65], s[62:63], s[60:61]
	s_cmp_eq_u64 s[64:65], 0
	s_cbranch_scc1 .Lq_locked_k0
	s_andn2_b64 s[64:65], s[60:61], s[62:63]
	s_not_b64 s[64:65], s[64:65]
	v_mov_b32_e32 v16, s64
	v_mov_b32_e32 v17, s65
	ds_and_b64 v30, v[16:17]
	s_sleep 2
	s_branch .Lq_lock_k0
.Lq_locked_k0:
	s_mov_b64 exec, s[54:55]
	ds_read_b128 v[82:85], v21
	ds_read_b128 v[86:89], v21 offset:32
	ds_read_b128 v[90:93], v21 offset:64
	ds_read_b128 v[94:97], v21 offset:96
	ds_read_b128 v[34:37], v21 offset:128
	ds_read_b128 v[38:41], v21 offset:160
	ds_read_b128 v[42:45], v21 offset:192
	ds_read_b128 v[46:49], v21 offset:224
	ds_read_b32 v28, v32
	s_waitcnt lgkmcnt(0)
	v_add_f32_e32 v82, v82, v66
	v_add_f32_e32 v83, v83, v67
	v_add_f32_e32 v84, v84, v68
	v_add_f32_e32 v85, v85, v69
	v_add_f32_e32 v86, v86, v70
	v_add_f32_e32 v87, v87, v71
	v_add_f32_e32 v88, v88, v72
	v_add_f32_e32 v89, v89, v73
	v_add_f32_e32 v90, v90, v74
	v_add_f32_e32 v91, v91, v75
	v_add_f32_e32 v92, v92, v76
	v_add_f32_e32 v93, v93, v77
	v_add_f32_e32 v94, v94, v78
	v_add_f32_e32 v95, v95, v79
	v_add_f32_e32 v96, v96, v80
	v_add_f32_e32 v97, v97, v81
	v_add_f32_e32 v34, v34, v50
	v_add_f32_e32 v35, v35, v51
	v_add_f32_e32 v36, v36, v52
	v_add_f32_e32 v37, v37, v53
	v_add_f32_e32 v38, v38, v54
	v_add_f32_e32 v39, v39, v55
	v_add_f32_e32 v40, v40, v56
	v_add_f32_e32 v41, v41, v57
	v_add_f32_e32 v42, v42, v58
	v_add_f32_e32 v43, v43, v59
	v_add_f32_e32 v44, v44, v60
	v_add_f32_e32 v45, v45, v61
	v_add_f32_e32 v46, v46, v62
	v_add_f32_e32 v47, v47, v63
	v_add_f32_e32 v48, v48, v64
	v_add_f32_e32 v49, v49, v65
	v_add_f32_e32 v28, v28, v221
	ds_write_b128 v21, v[82:85]
	ds_write_b128 v21, v[86:89] offset:32
	ds_write_b128 v21, v[90:93] offset:64
	ds_write_b128 v21, v[94:97] offset:96
	ds_write_b128 v21, v[34:37] offset:128
	ds_write_b128 v21, v[38:41] offset:160
	ds_write_b128 v21, v[42:45] offset:192
	ds_write_b128 v21, v[46:49] offset:224
	ds_write_b32 v32, v28
	s_mov_b64 exec, 1
	s_not_b64 s[64:65], s[60:61]
	v_mov_b32_e32 v16, s64
	v_mov_b32_e32 v17, s65
	ds_and_b64 v30, v[16:17]
	s_mov_b64 exec, s[58:59]
	s_cmp_lg_u32 s85, s86
	s_cbranch_scc1 .Lq_nl1_k0
	s_min_u32 s14, s88, 63
	s_nop 3
	v_readlane_b32 s30, v33, s14
	s_and_b32 s30, s30, 0xff
	s_lshl_b32 s30, s30, 13
	s_add_u32 s64, s11, s30
	s_addc_u32 s65, s12, 0
	s_add_u32 s66, s8, s30
	s_addc_u32 s67, s9, 0
	global_load_dwordx4 v[162:165], v2, s[64:65]
	global_load_dwordx4 v[154:157], v2, s[64:65] offset:1024
	global_load_dwordx4 v[150:153], v2, s[64:65] offset:2048
	global_load_dwordx4 v[158:161], v2, s[64:65] offset:3072
	global_load_dwordx4 v[138:141], v2, s[66:67]
	global_load_dwordx4 v[122:125], v2, s[66:67] offset:1024
	global_load_dwordx4 v[110:113], v2, s[66:67] offset:2048
	global_load_dwordx4 v[106:109], v2, s[66:67] offset:3072
.Lq_nl1_k0:
	s_mov_b32 s68, s85
	s_cmp_lt_u32 s68, s86
	s_cbranch_scc1 .Lq_tk_k0
.Lq_visit_k1:
	s_lshr_b32 s84, s52, 1
	s_add_i32 s84, s84, 1
	s_cmp_ge_u32 s84, s89
	s_cbranch_scc1 .Lq_loop_end
	s_min_u32 s14, s84, 63
	s_nop 3
	v_readlane_b32 s0, v33, s14
	s_and_b32 s100, s0, 0xff
	s_lshr_b32 s68, s0, 8
	s_mov_b32 s91, s68
	s_add_i32 s1, s84, 1
	s_min_u32 s14, s1, 63
	s_nop 3
	v_readlane_b32 s86, v33, s14
	s_lshr_b32 s86, s86, 8
	s_cmp_ge_u32 s1, s89
	s_cselect_b32 s86, s10, s86
	s_add_i32 s87, s84, 1
	s_add_i32 s88, s84, 2

.Lq_wd_k1:
	v_mov_b32_e32 v4, v238
	v_mov_b32_e32 v5, v239
	v_mov_b32_e32 v6, v240
	v_mov_b32_e32 v7, v241
	v_mov_b32_e32 v8, v242
	v_mov_b32_e32 v9, v243
	v_mov_b32_e32 v10, v244
	v_mov_b32_e32 v11, v245
	v_mov_b32_e32 v12, v246
	v_mov_b32_e32 v13, v247
	v_mov_b32_e32 v14, v248
	v_mov_b32_e32 v15, v249
	v_mov_b32_e32 v98, v250
	v_mov_b32_e32 v99, v251
	v_mov_b32_e32 v100, v252
	v_mov_b32_e32 v101, v253
	v_bfe_u32 v28, s57, v18, 8
	v_lshl_add_u32 v218, s99, 6, v28
	v_mad_u32_u24 v21, v28, s82, v19
	v_mad_u32_u24 v32, v28, s82, v31
	v_and_b32_e32 v29, s18, v230
	v_cmp_ne_u32_e64 s[54:55], 0, v29
	s_and_b64 s[54:55], s[54:55], s[6:7]
	s_min_u32 s14, s85, 63
	s_nop 3
	v_readlane_b32 s30, v26, s14
	v_readlane_b32 s31, v27, s14
	v_bfe_u32 v28, s31, v18, 8
	v_lshl_add_u32 v29, s99, 6, v28
	v_mad_u32_u24 v29, v29, s47, v20
	global_load_dwordx4 v[238:241], v29, s[20:21]
	global_load_dwordx4 v[242:245], v29, s[20:21] offset:32
	global_load_dwordx4 v[246:249], v29, s[20:21] offset:64
	global_load_dwordx4 v[250:253], v29, s[20:21] offset:96
	s_lshl_b32 s0, s100, 6
	v_or_b32_e32 v237, s0, v206
	v_mov_b32_e32 v221, 0
	s_cmp_lg_u32 s100, s99
	s_cbranch_scc1 .Lq_s0n_k1
	v_and_b32_e32 v82, s18, v230
	v_cmp_ne_u32_e32 vcc, 0, v82
	s_and_b64 vcc, s[6:7], vcc
	v_mov_b32 v83, 0
	v_or_b32_e32 v16, 2, v237
	v_cndmask_b32_e32 v82, v236, v222, vcc
	v_sub_f32_e32 v82, v83, v82
	v_mov_b32_e32 v83, v82
	v_mov_b32_e32 v84, v82
	v_mov_b32_e32 v85, v82
	v_mov_b32_e32 v86, v82
	v_mov_b32_e32 v87, v82
	v_mov_b32_e32 v88, v82
	v_mov_b32_e32 v89, v82
	v_mov_b32_e32 v90, v82
	v_mov_b32_e32 v91, v82
	v_mov_b32_e32 v92, v82
	v_mov_b32_e32 v93, v82
	v_mov_b32_e32 v94, v82
	v_mov_b32_e32 v95, v82
	v_mov_b32_e32 v96, v82
	v_mov_b32_e32 v97, v82
	v_cmp_le_i32_e32 vcc, v237, v218
	v_or_b32_e32 v17, 3, v237
	v_mfma_f32_32x32x16_bf16 v[82:97], v[194:197], v[4:7], v[82:97]
	v_or_b32_e32 v30, 8, v237
	v_mfma_f32_32x32x16_bf16 v[82:97], v[190:193], v[8:11], v[82:97]
	v_mfma_f32_32x32x16_bf16 v[82:97], v[186:189], v[12:15], v[82:97]
	v_mfma_f32_32x32x16_bf16 v[82:97], v[182:185], v[98:101], v[82:97]
	s_nop 11
	v_exp_f32_e32 v82, v82
	v_exp_f32_e32 v83, v83
	v_exp_f32_e32 v84, v84
	v_exp_f32_e32 v85, v85
	v_exp_f32_e32 v86, v86
	v_cndmask_b32_e32 v82, 0, v82, vcc
	v_cmp_lt_i32_e32 vcc, v237, v218
	v_exp_f32_e32 v87, v87
	v_exp_f32_e32 v88, v88
	v_cndmask_b32_e32 v83, 0, v83, vcc
	v_cmp_le_i32_e32 vcc, v16, v218
	v_or_b32_e32 v16, 9, v237
	v_exp_f32_e32 v89, v89
	v_cndmask_b32_e32 v84, 0, v84, vcc
	v_cmp_le_i32_e32 vcc, v17, v218
	v_exp_f32_e32 v90, v90
	v_exp_f32_e32 v91, v91
	v_cndmask_b32_e32 v85, 0, v85, vcc
	v_cmp_le_i32_e32 vcc, v30, v218
	v_add_f32_e32 v221, v221, v82
	v_exp_f32_e32 v92, v92
	v_cndmask_b32_e32 v86, 0, v86, vcc
	v_cmp_le_i32_e32 vcc, v16, v218
	v_or_b32_e32 v16, 10, v237
	v_add_f32_e32 v221, v83, v221
	v_cndmask_b32_e32 v87, 0, v87, vcc
	v_cmp_le_i32_e32 vcc, v16, v218
	v_or_b32_e32 v16, 11, v237
	v_exp_f32_e32 v93, v93
	v_cndmask_b32_e32 v88, 0, v88, vcc
	v_cmp_le_i32_e32 vcc, v16, v218
	v_or_b32_e32 v16, 16, v237
	v_add_f32_e32 v221, v84, v221
	v_cndmask_b32_e32 v89, 0, v89, vcc
	v_cmp_le_i32_e32 vcc, v16, v218
	v_or_b32_e32 v16, 17, v237
	v_exp_f32_e32 v94, v94
	v_cndmask_b32_e32 v90, 0, v90, vcc
	v_cmp_le_i32_e32 vcc, v16, v218
	v_or_b32_e32 v16, 18, v237
	v_add_f32_e32 v221, v85, v221
	v_cndmask_b32_e32 v91, 0, v91, vcc
	v_cmp_le_i32_e32 vcc, v16, v218
	v_or_b32_e32 v16, 19, v237
	v_exp_f32_e32 v95, v95
	v_add_f32_e32 v221, v86, v221
	v_cndmask_b32_e32 v92, 0, v92, vcc
	v_cmp_le_i32_e32 vcc, v16, v218
	v_or_b32_e32 v16, 24, v237
	v_cvt_pk_bf16_f32 v82, v82, v83
	v_cvt_pk_bf16_f32 v83, v84, v85
	v_cvt_pk_bf16_f32 v84, v86, v87
	v_cvt_pk_bf16_f32 v85, v88, v89
	v_add_f32_e32 v221, v87, v221
	v_cndmask_b32_e32 v93, 0, v93, vcc
	v_cmp_le_i32_e32 vcc, v16, v218
	v_or_b32_e32 v16, 25, v237
	v_mfma_f32_32x32x16_bf16 v[66:81], v[134:137], v[82:85], 0
	v_add_f32_e32 v221, v88, v221
	v_cndmask_b32_e32 v94, 0, v94, vcc
	v_exp_f32_e32 v86, v96
	v_cmp_le_i32_e32 vcc, v16, v218
	v_or_b32_e32 v88, 26, v237
	v_add_f32_e32 v221, v89, v221
	v_cndmask_b32_e32 v87, 0, v95, vcc
	v_mfma_f32_32x32x16_bf16 v[50:65], v[130:133], v[82:85], 0
	v_cmp_le_i32_e32 vcc, v88, v218
	v_exp_f32_e32 v88, v97
	v_or_b32_e32 v82, 27, v237
	v_cndmask_b32_e32 v86, 0, v86, vcc
	v_cmp_le_i32_e32 vcc, v82, v218
	v_cvt_pk_bf16_f32 v82, v90, v91
	v_cvt_pk_bf16_f32 v83, v92, v93
	v_cndmask_b32_e32 v88, 0, v88, vcc
	v_cvt_pk_bf16_f32 v84, v94, v87
	v_cvt_pk_bf16_f32 v85, v86, v88
	v_add_f32_e32 v221, v90, v221
	v_add_f32_e32 v89, v91, v221
	v_mfma_f32_32x32x16_bf16 v[66:81], v[118:121], v[82:85], v[66:81]
	v_add_f32_e32 v89, v92, v89
	v_add_f32_e32 v89, v93, v89
	v_add_f32_e32 v89, v94, v89
	v_add_f32_e32 v87, v87, v89
	v_add_f32_e32 v86, v86, v87
	v_add_f32_e32 v221, v88, v86
	v_mfma_f32_32x32x16_bf16 v[50:65], v[102:105], v[82:85], v[50:65]
	s_branch .Lq_s0d_k1

.Lq_s0d_k1:
	s_cmp_lg_u32 s85, s86
	s_cbranch_scc1 .Lq_nl0_k1
	s_min_u32 s14, s87, 63
	s_nop 3
	v_readlane_b32 s30, v33, s14
	s_and_b32 s30, s30, 0xff
	s_lshl_b32 s30, s30, 13
	s_or_b32 s30, s30, 0x1000
	s_add_u32 s64, s11, s30
	s_addc_u32 s65, s12, 0
	s_add_u32 s66, s8, s30
	s_addc_u32 s67, s9, 0
	global_load_dwordx4 v[194:197], v2, s[64:65]
	global_load_dwordx4 v[190:193], v2, s[64:65] offset:1024
	global_load_dwordx4 v[186:189], v2, s[64:65] offset:2048
	global_load_dwordx4 v[182:185], v2, s[64:65] offset:3072
	global_load_dwordx4 v[134:137], v2, s[66:67]
	global_load_dwordx4 v[130:133], v2, s[66:67] offset:1024
	global_load_dwordx4 v[118:121], v2, s[66:67] offset:2048
	global_load_dwordx4 v[102:105], v2, s[66:67] offset:3072
	s_waitcnt vmcnt(20)
	s_branch .Lq_nl0d_k1

.Lq_nl0d_k1:
	s_lshl_b32 s0, s100, 6
	s_or_b32 s0, s0, 32
	v_or_b32_e32 v237, s0, v206
	s_cmp_lg_u32 s100, s99
	s_cbranch_scc1 .Lq_s1n_k1
	v_and_b32_e32 v82, s18, v230
	v_cmp_ne_u32_e32 vcc, 0, v82
	s_and_b64 vcc, s[6:7], vcc
	v_mov_b32 v83, 0
	v_or_b32_e32 v16, 2, v237
	v_cndmask_b32_e32 v82, v236, v222, vcc
	v_sub_f32_e32 v82, v83, v82
	v_mov_b32_e32 v83, v82
	v_mov_b32_e32 v84, v82
	v_mov_b32_e32 v85, v82
	v_mov_b32_e32 v86, v82
	v_mov_b32_e32 v87, v82
	v_mov_b32_e32 v88, v82
	v_mov_b32_e32 v89, v82
	v_mov_b32_e32 v90, v82
	v_mov_b32_e32 v91, v82
	v_mov_b32_e32 v92, v82
	v_mov_b32_e32 v93, v82
	v_mov_b32_e32 v94, v82
	v_mov_b32_e32 v95, v82
	v_mov_b32_e32 v96, v82
	v_mov_b32_e32 v97, v82
	v_cmp_le_i32_e32 vcc, v237, v218
	v_or_b32_e32 v17, 3, v237
	v_mfma_f32_32x32x16_bf16 v[82:97], v[178:181], v[4:7], v[82:97]
	v_or_b32_e32 v30, 8, v237
	v_mfma_f32_32x32x16_bf16 v[82:97], v[174:177], v[8:11], v[82:97]
	v_mfma_f32_32x32x16_bf16 v[82:97], v[170:173], v[12:15], v[82:97]
	v_mfma_f32_32x32x16_bf16 v[82:97], v[166:169], v[98:101], v[82:97]
	s_nop 11
	v_exp_f32_e32 v82, v82
	v_exp_f32_e32 v83, v83
	v_exp_f32_e32 v84, v84
	v_exp_f32_e32 v85, v85
	v_exp_f32_e32 v86, v86
	v_cndmask_b32_e32 v82, 0, v82, vcc
	v_cmp_lt_i32_e32 vcc, v237, v218
	v_exp_f32_e32 v87, v87
	v_exp_f32_e32 v88, v88
	v_cndmask_b32_e32 v83, 0, v83, vcc
	v_cmp_le_i32_e32 vcc, v16, v218
	v_or_b32_e32 v16, 9, v237
	v_exp_f32_e32 v89, v89
	v_cndmask_b32_e32 v84, 0, v84, vcc
	v_cmp_le_i32_e32 vcc, v17, v218
	v_exp_f32_e32 v90, v90
	v_exp_f32_e32 v91, v91
	v_cndmask_b32_e32 v85, 0, v85, vcc
	v_cmp_le_i32_e32 vcc, v30, v218
	v_add_f32_e32 v221, v221, v82
	v_exp_f32_e32 v92, v92
	v_cndmask_b32_e32 v86, 0, v86, vcc
	v_cmp_le_i32_e32 vcc, v16, v218
	v_or_b32_e32 v16, 10, v237
	v_add_f32_e32 v221, v83, v221
	v_cndmask_b32_e32 v87, 0, v87, vcc
	v_cmp_le_i32_e32 vcc, v16, v218
	v_or_b32_e32 v16, 11, v237
	v_exp_f32_e32 v93, v93
	v_cndmask_b32_e32 v88, 0, v88, vcc
	v_cmp_le_i32_e32 vcc, v16, v218
	v_or_b32_e32 v16, 16, v237
	v_add_f32_e32 v221, v84, v221
	v_cndmask_b32_e32 v89, 0, v89, vcc
	v_cmp_le_i32_e32 vcc, v16, v218
	v_or_b32_e32 v16, 17, v237
	v_exp_f32_e32 v94, v94
	v_cndmask_b32_e32 v90, 0, v90, vcc
	v_cmp_le_i32_e32 vcc, v16, v218
	v_or_b32_e32 v16, 18, v237
	v_add_f32_e32 v221, v85, v221
	v_cndmask_b32_e32 v91, 0, v91, vcc
	v_cmp_le_i32_e32 vcc, v16, v218
	v_or_b32_e32 v16, 19, v237
	v_exp_f32_e32 v95, v95
	v_add_f32_e32 v221, v86, v221
	v_cndmask_b32_e32 v92, 0, v92, vcc
	v_cmp_le_i32_e32 vcc, v16, v218
	v_or_b32_e32 v16, 24, v237
	v_cvt_pk_bf16_f32 v82, v82, v83
	v_cvt_pk_bf16_f32 v83, v84, v85
	v_cvt_pk_bf16_f32 v84, v86, v87
	v_cvt_pk_bf16_f32 v85, v88, v89
	v_add_f32_e32 v221, v87, v221
	v_cndmask_b32_e32 v93, 0, v93, vcc
	v_cmp_le_i32_e32 vcc, v16, v218
	v_or_b32_e32 v16, 25, v237
	v_mfma_f32_32x32x16_bf16 v[66:81], v[146:149], v[82:85], v[66:81]
	v_add_f32_e32 v221, v88, v221
	v_cndmask_b32_e32 v94, 0, v94, vcc
	v_exp_f32_e32 v86, v96
	v_cmp_le_i32_e32 vcc, v16, v218
	v_or_b32_e32 v88, 26, v237
	v_add_f32_e32 v221, v89, v221
	v_cndmask_b32_e32 v87, 0, v95, vcc
	v_mfma_f32_32x32x16_bf16 v[50:65], v[142:145], v[82:85], v[50:65]
	v_cmp_le_i32_e32 vcc, v88, v218
	v_exp_f32_e32 v88, v97
	v_or_b32_e32 v82, 27, v237
	v_cndmask_b32_e32 v86, 0, v86, vcc
	v_cmp_le_i32_e32 vcc, v82, v218
	v_cvt_pk_bf16_f32 v82, v90, v91
	v_cvt_pk_bf16_f32 v83, v92, v93
	v_cndmask_b32_e32 v88, 0, v88, vcc
	v_cvt_pk_bf16_f32 v84, v94, v87
	v_cvt_pk_bf16_f32 v85, v86, v88
	v_add_f32_e32 v221, v90, v221
	v_add_f32_e32 v89, v91, v221
	v_mfma_f32_32x32x16_bf16 v[66:81], v[126:129], v[82:85], v[66:81]
	v_add_f32_e32 v89, v92, v89
	v_add_f32_e32 v89, v93, v89
	v_add_f32_e32 v89, v94, v89
	v_add_f32_e32 v87, v87, v89
	v_add_f32_e32 v86, v86, v87
	v_add_f32_e32 v221, v88, v86
	v_mfma_f32_32x32x16_bf16 v[50:65], v[114:117], v[82:85], v[50:65]
	s_branch .Lq_s1d_k1

.Lq_locked_k1:
	s_mov_b64 exec, s[54:55]
	ds_read_b128 v[82:85], v21
	ds_read_b128 v[86:89], v21 offset:32
	ds_read_b128 v[90:93], v21 offset:64
	ds_read_b128 v[94:97], v21 offset:96
	ds_read_b128 v[34:37], v21 offset:128
	ds_read_b128 v[38:41], v21 offset:160
	ds_read_b128 v[42:45], v21 offset:192
	ds_read_b128 v[46:49], v21 offset:224
	ds_read_b32 v28, v32
	s_waitcnt lgkmcnt(0)
	v_add_f32_e32 v82, v82, v66
	v_add_f32_e32 v83, v83, v67
	v_add_f32_e32 v84, v84, v68
	v_add_f32_e32 v85, v85, v69
	v_add_f32_e32 v86, v86, v70
	v_add_f32_e32 v87, v87, v71
	v_add_f32_e32 v88, v88, v72
	v_add_f32_e32 v89, v89, v73
	v_add_f32_e32 v90, v90, v74
	v_add_f32_e32 v91, v91, v75
	v_add_f32_e32 v92, v92, v76
	v_add_f32_e32 v93, v93, v77
	v_add_f32_e32 v94, v94, v78
	v_add_f32_e32 v95, v95, v79
	v_add_f32_e32 v96, v96, v80
	v_add_f32_e32 v97, v97, v81
	v_add_f32_e32 v34, v34, v50
	v_add_f32_e32 v35, v35, v51
	v_add_f32_e32 v36, v36, v52
	v_add_f32_e32 v37, v37, v53
	v_add_f32_e32 v38, v38, v54
	v_add_f32_e32 v39, v39, v55
	v_add_f32_e32 v40, v40, v56
	v_add_f32_e32 v41, v41, v57
	v_add_f32_e32 v42, v42, v58
	v_add_f32_e32 v43, v43, v59
	v_add_f32_e32 v44, v44, v60
	v_add_f32_e32 v45, v45, v61
	v_add_f32_e32 v46, v46, v62
	v_add_f32_e32 v47, v47, v63
	v_add_f32_e32 v48, v48, v64
	v_add_f32_e32 v49, v49, v65
	v_add_f32_e32 v28, v28, v221
	ds_write_b128 v21, v[82:85]
	ds_write_b128 v21, v[86:89] offset:32
	ds_write_b128 v21, v[90:93] offset:64
	ds_write_b128 v21, v[94:97] offset:96
	ds_write_b128 v21, v[34:37] offset:128
	ds_write_b128 v21, v[38:41] offset:160
	ds_write_b128 v21, v[42:45] offset:192
	ds_write_b128 v21, v[46:49] offset:224
	ds_write_b32 v32, v28
	s_mov_b64 exec, 1
	s_not_b64 s[64:65], s[60:61]
	v_mov_b32_e32 v16, s64
	v_mov_b32_e32 v17, s65
	ds_and_b64 v30, v[16:17]
	s_mov_b64 exec, s[58:59]
	s_cmp_lg_u32 s85, s86
	s_cbranch_scc1 .Lq_nl1_k1
	s_min_u32 s14, s88, 63
	s_nop 3
	v_readlane_b32 s30, v33, s14
	s_and_b32 s30, s30, 0xff
	s_lshl_b32 s30, s30, 13
	s_add_u32 s64, s11, s30
	s_addc_u32 s65, s12, 0
	s_add_u32 s66, s8, s30
	s_addc_u32 s67, s9, 0
	global_load_dwordx4 v[178:181], v2, s[64:65]
	global_load_dwordx4 v[174:177], v2, s[64:65] offset:1024
	global_load_dwordx4 v[170:173], v2, s[64:65] offset:2048
	global_load_dwordx4 v[166:169], v2, s[64:65] offset:3072
	global_load_dwordx4 v[146:149], v2, s[66:67]
	global_load_dwordx4 v[142:145], v2, s[66:67] offset:1024
	global_load_dwordx4 v[126:129], v2, s[66:67] offset:2048
	global_load_dwordx4 v[114:117], v2, s[66:67] offset:3072

.Lq_visit_k2:
	s_lshr_b32 s84, s52, 1
	s_add_i32 s84, s84, 2
	s_cmp_ge_u32 s84, s89
	s_cbranch_scc1 .Lq_loop_end
	s_min_u32 s14, s84, 63
	s_nop 3
	v_readlane_b32 s0, v33, s14
	s_and_b32 s100, s0, 0xff
	s_lshr_b32 s68, s0, 8
	s_mov_b32 s91, s68
	s_add_i32 s1, s84, 1
	s_min_u32 s14, s1, 63
	s_nop 3
	v_readlane_b32 s86, v33, s14
	s_lshr_b32 s86, s86, 8
	s_cmp_ge_u32 s1, s89
	s_cselect_b32 s86, s10, s86
	s_add_i32 s87, s84, 1
	s_add_i32 s88, s84, 2

.Lq_wd_k2:
	v_mov_b32_e32 v4, v238
	v_mov_b32_e32 v5, v239
	v_mov_b32_e32 v6, v240
	v_mov_b32_e32 v7, v241
	v_mov_b32_e32 v8, v242
	v_mov_b32_e32 v9, v243
	v_mov_b32_e32 v10, v244
	v_mov_b32_e32 v11, v245
	v_mov_b32_e32 v12, v246
	v_mov_b32_e32 v13, v247
	v_mov_b32_e32 v14, v248
	v_mov_b32_e32 v15, v249
	v_mov_b32_e32 v98, v250
	v_mov_b32_e32 v99, v251
	v_mov_b32_e32 v100, v252
	v_mov_b32_e32 v101, v253
	v_bfe_u32 v28, s57, v18, 8
	v_lshl_add_u32 v218, s99, 6, v28
	v_mad_u32_u24 v21, v28, s82, v19
	v_mad_u32_u24 v32, v28, s82, v31
	v_and_b32_e32 v29, s18, v230
	v_cmp_ne_u32_e64 s[54:55], 0, v29
	s_and_b64 s[54:55], s[54:55], s[6:7]
	s_min_u32 s14, s85, 63
	s_nop 3
	v_readlane_b32 s30, v26, s14
	v_readlane_b32 s31, v27, s14
	v_bfe_u32 v28, s31, v18, 8
	v_lshl_add_u32 v29, s99, 6, v28
	v_mad_u32_u24 v29, v29, s47, v20
	global_load_dwordx4 v[238:241], v29, s[20:21]
	global_load_dwordx4 v[242:245], v29, s[20:21] offset:32
	global_load_dwordx4 v[246:249], v29, s[20:21] offset:64
	global_load_dwordx4 v[250:253], v29, s[20:21] offset:96
	s_lshl_b32 s0, s100, 6
	v_or_b32_e32 v237, s0, v206
	v_mov_b32_e32 v221, 0
	s_cmp_lg_u32 s100, s99
	s_cbranch_scc1 .Lq_s0n_k2
	v_and_b32_e32 v82, s18, v230
	v_cmp_ne_u32_e32 vcc, 0, v82
	s_and_b64 vcc, s[6:7], vcc
	v_mov_b32 v83, 0
	v_or_b32_e32 v16, 2, v237
	v_cndmask_b32_e32 v82, v236, v222, vcc
	v_sub_f32_e32 v82, v83, v82
	v_mov_b32_e32 v83, v82
	v_mov_b32_e32 v84, v82
	v_mov_b32_e32 v85, v82
	v_mov_b32_e32 v86, v82
	v_mov_b32_e32 v87, v82
	v_mov_b32_e32 v88, v82
	v_mov_b32_e32 v89, v82
	v_mov_b32_e32 v90, v82
	v_mov_b32_e32 v91, v82
	v_mov_b32_e32 v92, v82
	v_mov_b32_e32 v93, v82
	v_mov_b32_e32 v94, v82
	v_mov_b32_e32 v95, v82
	v_mov_b32_e32 v96, v82
	v_mov_b32_e32 v97, v82
	v_cmp_le_i32_e32 vcc, v237, v218
	v_or_b32_e32 v17, 3, v237
	v_mfma_f32_32x32x16_bf16 v[82:97], v[162:165], v[4:7], v[82:97]
	v_or_b32_e32 v30, 8, v237
	v_mfma_f32_32x32x16_bf16 v[82:97], v[154:157], v[8:11], v[82:97]
	v_mfma_f32_32x32x16_bf16 v[82:97], v[150:153], v[12:15], v[82:97]
	v_mfma_f32_32x32x16_bf16 v[82:97], v[158:161], v[98:101], v[82:97]
	s_nop 11
	v_exp_f32_e32 v82, v82
	v_exp_f32_e32 v83, v83
	v_exp_f32_e32 v84, v84
	v_exp_f32_e32 v85, v85
	v_exp_f32_e32 v86, v86
	v_cndmask_b32_e32 v82, 0, v82, vcc
	v_cmp_lt_i32_e32 vcc, v237, v218
	v_exp_f32_e32 v87, v87
	v_exp_f32_e32 v88, v88
	v_cndmask_b32_e32 v83, 0, v83, vcc
	v_cmp_le_i32_e32 vcc, v16, v218
	v_or_b32_e32 v16, 9, v237
	v_exp_f32_e32 v89, v89
	v_cndmask_b32_e32 v84, 0, v84, vcc
	v_cmp_le_i32_e32 vcc, v17, v218
	v_exp_f32_e32 v90, v90
	v_exp_f32_e32 v91, v91
	v_cndmask_b32_e32 v85, 0, v85, vcc
	v_cmp_le_i32_e32 vcc, v30, v218
	v_add_f32_e32 v221, v221, v82
	v_exp_f32_e32 v92, v92
	v_cndmask_b32_e32 v86, 0, v86, vcc
	v_cmp_le_i32_e32 vcc, v16, v218
	v_or_b32_e32 v16, 10, v237
	v_add_f32_e32 v221, v83, v221
	v_cndmask_b32_e32 v87, 0, v87, vcc
	v_cmp_le_i32_e32 vcc, v16, v218
	v_or_b32_e32 v16, 11, v237
	v_exp_f32_e32 v93, v93
	v_cndmask_b32_e32 v88, 0, v88, vcc
	v_cmp_le_i32_e32 vcc, v16, v218
	v_or_b32_e32 v16, 16, v237
	v_add_f32_e32 v221, v84, v221
	v_cndmask_b32_e32 v89, 0, v89, vcc
	v_cmp_le_i32_e32 vcc, v16, v218
	v_or_b32_e32 v16, 17, v237
	v_exp_f32_e32 v94, v94
	v_cndmask_b32_e32 v90, 0, v90, vcc
	v_cmp_le_i32_e32 vcc, v16, v218
	v_or_b32_e32 v16, 18, v237
	v_add_f32_e32 v221, v85, v221
	v_cndmask_b32_e32 v91, 0, v91, vcc
	v_cmp_le_i32_e32 vcc, v16, v218
	v_or_b32_e32 v16, 19, v237
	v_exp_f32_e32 v95, v95
	v_add_f32_e32 v221, v86, v221
	v_cndmask_b32_e32 v92, 0, v92, vcc
	v_cmp_le_i32_e32 vcc, v16, v218
	v_or_b32_e32 v16, 24, v237
	v_cvt_pk_bf16_f32 v82, v82, v83
	v_cvt_pk_bf16_f32 v83, v84, v85
	v_cvt_pk_bf16_f32 v84, v86, v87
	v_cvt_pk_bf16_f32 v85, v88, v89
	v_add_f32_e32 v221, v87, v221
	v_cndmask_b32_e32 v93, 0, v93, vcc
	v_cmp_le_i32_e32 vcc, v16, v218
	v_or_b32_e32 v16, 25, v237
	v_mfma_f32_32x32x16_bf16 v[66:81], v[138:141], v[82:85], 0
	v_add_f32_e32 v221, v88, v221
	v_cndmask_b32_e32 v94, 0, v94, vcc
	v_exp_f32_e32 v86, v96
	v_cmp_le_i32_e32 vcc, v16, v218
	v_or_b32_e32 v88, 26, v237
	v_add_f32_e32 v221, v89, v221
	v_cndmask_b32_e32 v87, 0, v95, vcc
	v_mfma_f32_32x32x16_bf16 v[50:65], v[122:125], v[82:85], 0
	v_cmp_le_i32_e32 vcc, v88, v218
	v_exp_f32_e32 v88, v97
	v_or_b32_e32 v82, 27, v237
	v_cndmask_b32_e32 v86, 0, v86, vcc
	v_cmp_le_i32_e32 vcc, v82, v218
	v_cvt_pk_bf16_f32 v82, v90, v91
	v_cvt_pk_bf16_f32 v83, v92, v93
	v_cndmask_b32_e32 v88, 0, v88, vcc
	v_cvt_pk_bf16_f32 v84, v94, v87
	v_cvt_pk_bf16_f32 v85, v86, v88
	v_add_f32_e32 v221, v90, v221
	v_add_f32_e32 v89, v91, v221
	v_mfma_f32_32x32x16_bf16 v[66:81], v[110:113], v[82:85], v[66:81]
	v_add_f32_e32 v89, v92, v89
	v_add_f32_e32 v89, v93, v89
	v_add_f32_e32 v89, v94, v89
	v_add_f32_e32 v87, v87, v89
	v_add_f32_e32 v86, v86, v87
	v_add_f32_e32 v221, v88, v86
	v_mfma_f32_32x32x16_bf16 v[50:65], v[106:109], v[82:85], v[50:65]
	s_branch .Lq_s0d_k2

.Lq_s0d_k2:
	s_cmp_lg_u32 s85, s86
	s_cbranch_scc1 .Lq_nl0_k2
	s_min_u32 s14, s87, 63
	s_nop 3
	v_readlane_b32 s30, v33, s14
	s_and_b32 s30, s30, 0xff
	s_lshl_b32 s30, s30, 13
	s_or_b32 s30, s30, 0x1000
	s_add_u32 s64, s11, s30
	s_addc_u32 s65, s12, 0
	s_add_u32 s66, s8, s30
	s_addc_u32 s67, s9, 0
	global_load_dwordx4 v[162:165], v2, s[64:65]
	global_load_dwordx4 v[154:157], v2, s[64:65] offset:1024
	global_load_dwordx4 v[150:153], v2, s[64:65] offset:2048
	global_load_dwordx4 v[158:161], v2, s[64:65] offset:3072
	global_load_dwordx4 v[138:141], v2, s[66:67]
	global_load_dwordx4 v[122:125], v2, s[66:67] offset:1024
	global_load_dwordx4 v[110:113], v2, s[66:67] offset:2048
	global_load_dwordx4 v[106:109], v2, s[66:67] offset:3072
	s_waitcnt vmcnt(20)
	s_branch .Lq_nl0d_k2

.Lq_nl0d_k2:
	s_lshl_b32 s0, s100, 6
	s_or_b32 s0, s0, 32
	v_or_b32_e32 v237, s0, v206
	s_cmp_lg_u32 s100, s99
	s_cbranch_scc1 .Lq_s1n_k2
	v_and_b32_e32 v82, s18, v230
	v_cmp_ne_u32_e32 vcc, 0, v82
	s_and_b64 vcc, s[6:7], vcc
	v_mov_b32 v83, 0
	v_or_b32_e32 v16, 2, v237
	v_cndmask_b32_e32 v82, v236, v222, vcc
	v_sub_f32_e32 v82, v83, v82
	v_mov_b32_e32 v83, v82
	v_mov_b32_e32 v84, v82
	v_mov_b32_e32 v85, v82
	v_mov_b32_e32 v86, v82
	v_mov_b32_e32 v87, v82
	v_mov_b32_e32 v88, v82
	v_mov_b32_e32 v89, v82
	v_mov_b32_e32 v90, v82
	v_mov_b32_e32 v91, v82
	v_mov_b32_e32 v92, v82
	v_mov_b32_e32 v93, v82
	v_mov_b32_e32 v94, v82
	v_mov_b32_e32 v95, v82
	v_mov_b32_e32 v96, v82
	v_mov_b32_e32 v97, v82
	v_cmp_le_i32_e32 vcc, v237, v218
	v_or_b32_e32 v17, 3, v237
	v_mfma_f32_32x32x16_bf16 v[82:97], v[194:197], v[4:7], v[82:97]
	v_or_b32_e32 v30, 8, v237
	v_mfma_f32_32x32x16_bf16 v[82:97], v[190:193], v[8:11], v[82:97]
	v_mfma_f32_32x32x16_bf16 v[82:97], v[186:189], v[12:15], v[82:97]
	v_mfma_f32_32x32x16_bf16 v[82:97], v[182:185], v[98:101], v[82:97]
	s_nop 11
	v_exp_f32_e32 v82, v82
	v_exp_f32_e32 v83, v83
	v_exp_f32_e32 v84, v84
	v_exp_f32_e32 v85, v85
	v_exp_f32_e32 v86, v86
	v_cndmask_b32_e32 v82, 0, v82, vcc
	v_cmp_lt_i32_e32 vcc, v237, v218
	v_exp_f32_e32 v87, v87
	v_exp_f32_e32 v88, v88
	v_cndmask_b32_e32 v83, 0, v83, vcc
	v_cmp_le_i32_e32 vcc, v16, v218
	v_or_b32_e32 v16, 9, v237
	v_exp_f32_e32 v89, v89
	v_cndmask_b32_e32 v84, 0, v84, vcc
	v_cmp_le_i32_e32 vcc, v17, v218
	v_exp_f32_e32 v90, v90
	v_exp_f32_e32 v91, v91
	v_cndmask_b32_e32 v85, 0, v85, vcc
	v_cmp_le_i32_e32 vcc, v30, v218
	v_add_f32_e32 v221, v221, v82
	v_exp_f32_e32 v92, v92
	v_cndmask_b32_e32 v86, 0, v86, vcc
	v_cmp_le_i32_e32 vcc, v16, v218
	v_or_b32_e32 v16, 10, v237
	v_add_f32_e32 v221, v83, v221
	v_cndmask_b32_e32 v87, 0, v87, vcc
	v_cmp_le_i32_e32 vcc, v16, v218
	v_or_b32_e32 v16, 11, v237
	v_exp_f32_e32 v93, v93
	v_cndmask_b32_e32 v88, 0, v88, vcc
	v_cmp_le_i32_e32 vcc, v16, v218
	v_or_b32_e32 v16, 16, v237
	v_add_f32_e32 v221, v84, v221
	v_cndmask_b32_e32 v89, 0, v89, vcc
	v_cmp_le_i32_e32 vcc, v16, v218
	v_or_b32_e32 v16, 17, v237
	v_exp_f32_e32 v94, v94
	v_cndmask_b32_e32 v90, 0, v90, vcc
	v_cmp_le_i32_e32 vcc, v16, v218
	v_or_b32_e32 v16, 18, v237
	v_add_f32_e32 v221, v85, v221
	v_cndmask_b32_e32 v91, 0, v91, vcc
	v_cmp_le_i32_e32 vcc, v16, v218
	v_or_b32_e32 v16, 19, v237
	v_exp_f32_e32 v95, v95
	v_add_f32_e32 v221, v86, v221
	v_cndmask_b32_e32 v92, 0, v92, vcc
	v_cmp_le_i32_e32 vcc, v16, v218
	v_or_b32_e32 v16, 24, v237
	v_cvt_pk_bf16_f32 v82, v82, v83
	v_cvt_pk_bf16_f32 v83, v84, v85
	v_cvt_pk_bf16_f32 v84, v86, v87
	v_cvt_pk_bf16_f32 v85, v88, v89
	v_add_f32_e32 v221, v87, v221
	v_cndmask_b32_e32 v93, 0, v93, vcc
	v_cmp_le_i32_e32 vcc, v16, v218
	v_or_b32_e32 v16, 25, v237
	v_mfma_f32_32x32x16_bf16 v[66:81], v[134:137], v[82:85], v[66:81]
	v_add_f32_e32 v221, v88, v221
	v_cndmask_b32_e32 v94, 0, v94, vcc
	v_exp_f32_e32 v86, v96
	v_cmp_le_i32_e32 vcc, v16, v218
	v_or_b32_e32 v88, 26, v237
	v_add_f32_e32 v221, v89, v221
	v_cndmask_b32_e32 v87, 0, v95, vcc
	v_mfma_f32_32x32x16_bf16 v[50:65], v[130:133], v[82:85], v[50:65]
	v_cmp_le_i32_e32 vcc, v88, v218
	v_exp_f32_e32 v88, v97
	v_or_b32_e32 v82, 27, v237
	v_cndmask_b32_e32 v86, 0, v86, vcc
	v_cmp_le_i32_e32 vcc, v82, v218
	v_cvt_pk_bf16_f32 v82, v90, v91
	v_cvt_pk_bf16_f32 v83, v92, v93
	v_cndmask_b32_e32 v88, 0, v88, vcc
	v_cvt_pk_bf16_f32 v84, v94, v87
	v_cvt_pk_bf16_f32 v85, v86, v88
	v_add_f32_e32 v221, v90, v221
	v_add_f32_e32 v89, v91, v221
	v_mfma_f32_32x32x16_bf16 v[66:81], v[118:121], v[82:85], v[66:81]
	v_add_f32_e32 v89, v92, v89
	v_add_f32_e32 v89, v93, v89
	v_add_f32_e32 v89, v94, v89
	v_add_f32_e32 v87, v87, v89
	v_add_f32_e32 v86, v86, v87
	v_add_f32_e32 v221, v88, v86
	v_mfma_f32_32x32x16_bf16 v[50:65], v[102:105], v[82:85], v[50:65]
	s_branch .Lq_s1d_k2

.Lq_locked_k2:
	s_mov_b64 exec, s[54:55]
	ds_read_b128 v[82:85], v21
	ds_read_b128 v[86:89], v21 offset:32
	ds_read_b128 v[90:93], v21 offset:64
	ds_read_b128 v[94:97], v21 offset:96
	ds_read_b128 v[34:37], v21 offset:128
	ds_read_b128 v[38:41], v21 offset:160
	ds_read_b128 v[42:45], v21 offset:192
	ds_read_b128 v[46:49], v21 offset:224
	ds_read_b32 v28, v32
	s_waitcnt lgkmcnt(0)
	v_add_f32_e32 v82, v82, v66
	v_add_f32_e32 v83, v83, v67
	v_add_f32_e32 v84, v84, v68
	v_add_f32_e32 v85, v85, v69
	v_add_f32_e32 v86, v86, v70
	v_add_f32_e32 v87, v87, v71
	v_add_f32_e32 v88, v88, v72
	v_add_f32_e32 v89, v89, v73
	v_add_f32_e32 v90, v90, v74
	v_add_f32_e32 v91, v91, v75
	v_add_f32_e32 v92, v92, v76
	v_add_f32_e32 v93, v93, v77
	v_add_f32_e32 v94, v94, v78
	v_add_f32_e32 v95, v95, v79
	v_add_f32_e32 v96, v96, v80
	v_add_f32_e32 v97, v97, v81
	v_add_f32_e32 v34, v34, v50
	v_add_f32_e32 v35, v35, v51
	v_add_f32_e32 v36, v36, v52
	v_add_f32_e32 v37, v37, v53
	v_add_f32_e32 v38, v38, v54
	v_add_f32_e32 v39, v39, v55
	v_add_f32_e32 v40, v40, v56
	v_add_f32_e32 v41, v41, v57
	v_add_f32_e32 v42, v42, v58
	v_add_f32_e32 v43, v43, v59
	v_add_f32_e32 v44, v44, v60
	v_add_f32_e32 v45, v45, v61
	v_add_f32_e32 v46, v46, v62
	v_add_f32_e32 v47, v47, v63
	v_add_f32_e32 v48, v48, v64
	v_add_f32_e32 v49, v49, v65
	v_add_f32_e32 v28, v28, v221
	ds_write_b128 v21, v[82:85]
	ds_write_b128 v21, v[86:89] offset:32
	ds_write_b128 v21, v[90:93] offset:64
	ds_write_b128 v21, v[94:97] offset:96
	ds_write_b128 v21, v[34:37] offset:128
	ds_write_b128 v21, v[38:41] offset:160
	ds_write_b128 v21, v[42:45] offset:192
	ds_write_b128 v21, v[46:49] offset:224
	ds_write_b32 v32, v28
	s_mov_b64 exec, 1
	s_not_b64 s[64:65], s[60:61]
	v_mov_b32_e32 v16, s64
	v_mov_b32_e32 v17, s65
	ds_and_b64 v30, v[16:17]
	s_mov_b64 exec, s[58:59]
	s_cmp_lg_u32 s85, s86
	s_cbranch_scc1 .Lq_nl1_k2
	s_min_u32 s14, s88, 63
	s_nop 3
	v_readlane_b32 s30, v33, s14
	s_and_b32 s30, s30, 0xff
	s_lshl_b32 s30, s30, 13
	s_add_u32 s64, s11, s30
	s_addc_u32 s65, s12, 0
	s_add_u32 s66, s8, s30
	s_addc_u32 s67, s9, 0
	global_load_dwordx4 v[194:197], v2, s[64:65]
	global_load_dwordx4 v[190:193], v2, s[64:65] offset:1024
	global_load_dwordx4 v[186:189], v2, s[64:65] offset:2048
	global_load_dwordx4 v[182:185], v2, s[64:65] offset:3072
	global_load_dwordx4 v[134:137], v2, s[66:67]
	global_load_dwordx4 v[130:133], v2, s[66:67] offset:1024
	global_load_dwordx4 v[118:121], v2, s[66:67] offset:2048
	global_load_dwordx4 v[102:105], v2, s[66:67] offset:3072
.Lq_nl1_k2:
	s_mov_b32 s68, s85
	s_cmp_lt_u32 s68, s86
	s_cbranch_scc1 .Lq_tk_k2
	s_add_i32 s52, s52, 6
	s_branch .Lq_loop
